# NSA units issue their next-unit queue pop at the start of the window loop instead of at unit start (shorter reservation, latency still hidden)
# speedup vs baseline: 1.0076x; 1.0076x over previous
; DI void phase_attn_fast(Frame& F, int l) {
;     ...
;     if (tid == 0) qidx[0] = (int)atomicAdd(ctr, 1u);
;     for (;;) {
;         __syncthreads();
;         const int i = qidx[0];
;         if (i >= 1024) break;
;         unsigned nxt = 0u; if (tid == 0) nxt = atomicAdd(ctr, 1u);
;         int tidu = tid; asm volatile("" : "+v"(tidu));
;         if (i < 512) { const int k = i & 31; unit_mla(F, k >> 3, k & 7, 15 - (i >> 5), tidu); }
.LBB0_1333:
	v_readlane_b32 s10, v254, 14
	s_waitcnt lgkmcnt(0)
	s_barrier
	v_mov_b32_e32 v0, s10
	ds_read_b32 v0, v0
	s_movk_i32 s10, 0x3ff
	s_waitcnt lgkmcnt(0)
	v_cmp_lt_i32_e64 s[44:45], s10, v0
	v_readfirstlane_b32 s88, v0
	s_and_b64 vcc, exec, s[44:45]
	s_cbranch_vccnz .LBB0_1380
	v_mov_b32_e32 v200, 0
	s_cmpk_gt_i32 s88, 0x1ff
	s_cbranch_scc1 .Lpop_skip
	s_and_saveexec_b64 s[10:11], s[74:75]
	s_cbranch_execz .LBB0_1338
	s_mov_b64 s[46:47], exec
	v_mbcnt_lo_u32_b32 v0, s46, 0
	v_mbcnt_hi_u32_b32 v0, s47, v0
	v_cmp_eq_u32_e32 vcc, 0, v0
	s_and_saveexec_b64 s[16:17], vcc
	s_cbranch_execz .LBB0_1337
	s_bcnt1_i32_b64 s22, s[46:47]
	v_mov_b32_e32 v2, s22
	v_readlane_b32 s22, v254, 63
	v_readlane_b32 s23, v255, 0
	s_nop 4
	global_atomic_add v200, v1, v2, s[22:23] sc0

; DI void phase_attn_fast(Frame& F, int l) {
;     ...
;         if (i < 512) { const int k = i & 31; unit_mla(F, k >> 3, k & 7, 15 - (i >> 5), tidu); }
;         else {
;             if (!cmp_ok) {
;                 if (tid == 0) { while (__hip_atomic_load(done, __ATOMIC_RELAXED, __HIP_MEMORY_SCOPE_AGENT) < 16u) __builtin_amdgcn_s_sleep(8); }
;                 __syncthreads(); __builtin_amdgcn_fence(__ATOMIC_ACQUIRE, "agent"); cmp_ok = true;
;             }
.Lpop_skip:
	s_xor_b64 s[16:17], s[8:9], -1
	v_mov_b32_e32 v201, v184
	s_mov_b64 s[10:11], -1
	s_cmpk_gt_i32 s88, 0x1ff
	s_mov_b64 s[46:47], -1
	s_cbranch_scc0 .LBB0_1477
	s_andn2_b64 vcc, exec, s[16:17]
	s_mov_b32 s53, 0xefa18f08
	s_cbranch_vccnz .LBB0_1344
	s_and_saveexec_b64 s[16:17], s[74:75]
	s_cbranch_execz .LBB0_1343
	global_load_dword v0, v1, s[70:71] sc1
	s_waitcnt vmcnt(0)
	v_cmp_lt_u32_e32 vcc, 15, v0
	s_cbranch_vccnz .LBB0_1343

; DI int tid_now() { int t = threadIdx.x; asm volatile("" : "+v"(t)); return t; }
;     DI float* h() const { return (float*)(__attribute__((address_space(1))) float*)kp->out; }
; DI void unit_nsa(Frame& F, int b, int g, int qt, int tid) {
;     ...
;     { const int r = tid_now() & 31, h = (tid_now() >> 5) & 1; CfNsa<false> cw{Q, O, m, l, t, r, h, sl2, 0ull}; att_pipe<false>(KB, VB, zb + Z_KW + g * 64, ZP, zb + Z_VW + g * 64, ZP, nullptr, TlRangeDesc{qt >= 8 ? qt - 8 : 0, qt}, cw, tid); }
; DI void phase_attn_fast(Frame& F, int l) {
;     ...
;         unsigned nxt = 0u; if (tid == 0) nxt = atomicAdd(ctr, 1u);
.LBB0_1456:
	v_readfirstlane_b32 s42, v213
	s_and_saveexec_b64 s[16:17], s[74:75]
	v_readlane_b32 s24, v254, 63
	v_readlane_b32 s25, v255, 0
	v_mov_b32_e32 v240, 1
	s_nop 4
	global_atomic_add v200, v1, v240, s[24:25] sc0
	s_or_b64 exec, exec, s[16:17]
	v_add_u32_e32 v170, v235, v236
	s_cmp_lt_i32 s23, 0
	s_cselect_b32 s24, s96, s23
	v_add_u32_e32 v10, s24, v210
	v_add_u32_e32 v12, s24, v211
	v_ashrrev_i32_e32 v11, 31, v10
	v_ashrrev_i32_e32 v13, 31, v12
	v_lshlrev_b64 v[10:11], 12, v[10:11]
	v_lshlrev_b64 v[12:13], 12, v[12:13]
	v_lshl_add_u64 v[192:193], v[188:189], 0, v[10:11]
	v_lshl_add_u64 v[194:195], v[190:191], 0, v[12:13]
